# SSD cumulative-decay stores plain only (separating the two previous edits)
# baseline (speedup 1.0000x reference)
; __device__ __forceinline__ void ssd_chunk_unit(LAS unsigned char* ldsb, int unit, const bf16* PROJ, bf16* XACT, const float* DTRAW, const float* conv_w, const float* conv_b, const float* dt_bias, const float* a_log, ...
;     ...
;         const int s = tid >> 2, hh = tid & 3, H = g * 4 + hh;
;         const float A = -__expf(a_log[H]);
;         const float raw = DTRAW[(size_t)(tok0 + s) * 8 + H] + dt_bias[H];
;         const float dtv = fmaxf(raw, 0.f) + log1pf(__expf(-fabsf(raw)));
;         float v = dtv * A;
; #pragma unroll
;         for (int o = 4; o < 64; o <<= 1) { const float y = __shfl_up(v, o); if (lane >= o) v += y; }
;         if (lane >= 60) WT[wave * 4 + hh] = v;
;         __syncthreads();
.LBB0_169:
	v_mov_b32_e32 v222, v208
	v_mov_b32_e32 v118, v209
	s_and_b32 s24, s55, 1
	s_lshl_b32 s63, s24, 2
	v_and_b32_e32 v6, 3, v118
	v_or_b32_e32 v4, s63, v6
	v_readlane_b32 s64, v235, 16
	v_lshlrev_b32_e32 v10, 2, v4
	v_readlane_b32 s65, v235, 17
	s_add_i32 s6, s55, 0xffffff00
	s_ashr_i32 s60, s6, 1
	s_lshl_b32 s12, s60, 7
	v_ashrrev_i32_e32 v5, 2, v118
	v_readlane_b32 s66, v235, 18
	global_load_dword v7, v10, s[64:65]
	v_readlane_b32 s67, v235, 19
	v_readlane_b32 s68, v235, 20
	v_readlane_b32 s69, v235, 21
	v_readlane_b32 s70, v235, 22
	v_readlane_b32 s71, v235, 23
	v_readlane_b32 s72, v235, 24
	v_readlane_b32 s73, v235, 25
	v_readlane_b32 s74, v235, 26
	v_readlane_b32 s75, v235, 27
	v_readlane_b32 s76, v235, 28
	v_readlane_b32 s77, v235, 29
	v_readlane_b32 s78, v235, 30
	v_readlane_b32 s79, v235, 31
	v_readlane_b32 s64, v235, 0
	v_readlane_b32 s78, v235, 14
	v_readlane_b32 s79, v235, 15
	s_mov_b32 s6, 0xbfb8aa3b
	v_readlane_b32 s65, v235, 1
	v_readlane_b32 s66, v235, 2
	v_readlane_b32 s67, v235, 3
	v_readlane_b32 s68, v235, 4
	v_readlane_b32 s69, v235, 5
	v_readlane_b32 s70, v235, 6
	v_readlane_b32 s71, v235, 7
	v_readlane_b32 s72, v235, 8
	v_readlane_b32 s73, v235, 9
	v_readlane_b32 s74, v235, 10
	v_readlane_b32 s75, v235, 11
	v_readlane_b32 s76, v235, 12
	v_readlane_b32 s77, v235, 13
	s_nop 0
	v_add_u32_e32 v2, s12, v5
	v_ashrrev_i32_e32 v3, 31, v2
	v_lshlrev_b64 v[2:3], 3, v[2:3]
	v_or_b32_e32 v2, v2, v4
	v_lshl_add_u64 v[8:9], v[2:3], 2, s[0:1]
	global_load_dword v8, v[8:9], off
	s_nop 0
	global_load_dword v9, v10, s[78:79]
	s_waitcnt vmcnt(0)
	v_mul_f32_e32 v7, 0x3fb8aa3b, v7
	v_exp_f32_e32 v7, v7
	v_add_f32_e32 v8, v8, v9
	v_max_f32_e32 v10, 0, v8
	v_mul_f32_e64 v8, |v8|, s6
	v_exp_f32_e32 v11, v8
	s_mov_b32 s6, 0x3f2aaaab
	v_add_f32_e32 v12, 1.0, v11
	v_add_f32_e32 v8, -1.0, v12
	v_sub_f32_e32 v9, v8, v12
	v_add_f32_e32 v9, 1.0, v9
	v_sub_f32_e32 v8, v11, v8
	v_add_f32_e32 v13, v8, v9
	v_frexp_mant_f32_e32 v8, v12
	v_cmp_gt_f32_e32 vcc, s6, v8
	v_cvt_f64_f32_e32 v[8:9], v12
	v_frexp_exp_i32_f64_e32 v8, v[8:9]
	v_subbrev_co_u32_e32 v8, vcc, 0, v8, vcc
	v_sub_u32_e32 v9, 0, v8
	v_ldexp_f32 v12, v12, v9
	v_ldexp_f32 v9, v13, v9
	v_add_f32_e32 v13, -1.0, v12
	v_add_f32_e32 v14, 1.0, v13
	v_sub_f32_e32 v14, v12, v14
	v_add_f32_e32 v14, v9, v14
	v_add_f32_e32 v15, v13, v14
	v_sub_f32_e32 v13, v15, v13
	v_sub_f32_e32 v13, v14, v13
	v_add_f32_e32 v14, 1.0, v12
	v_add_f32_e32 v16, -1.0, v14
	v_sub_f32_e32 v12, v12, v16
	v_add_f32_e32 v9, v9, v12
	v_add_f32_e32 v12, v14, v9
	v_sub_f32_e32 v14, v12, v14
	v_sub_f32_e32 v9, v9, v14
	v_rcp_f32_e32 v14, v12
	v_cvt_f32_i32_e32 v8, v8
	s_mov_b32 s6, 0x3f317218
	v_mul_f32_e32 v16, v15, v14
	v_mul_f32_e32 v17, v12, v16
	v_fma_f32 v18, v16, v12, -v17
	v_fmac_f32_e32 v18, v16, v9
	v_add_f32_e32 v19, v17, v18
	v_sub_f32_e32 v20, v15, v19
	v_sub_f32_e32 v15, v15, v20
	v_sub_f32_e32 v17, v19, v17
	v_sub_f32_e32 v15, v15, v19
	v_add_f32_e32 v13, v13, v15
	v_sub_f32_e32 v15, v17, v18
	v_add_f32_e32 v13, v15, v13
	v_add_f32_e32 v15, v20, v13
	v_mul_f32_e32 v17, v14, v15
	v_mul_f32_e32 v18, v12, v17
	v_fma_f32 v12, v17, v12, -v18
	v_fmac_f32_e32 v12, v17, v9
	v_sub_f32_e32 v9, v20, v15
	v_add_f32_e32 v9, v13, v9
	v_add_f32_e32 v13, v18, v12
	v_sub_f32_e32 v19, v15, v13
	v_sub_f32_e32 v15, v15, v19
	v_sub_f32_e32 v18, v13, v18
	v_sub_f32_e32 v13, v15, v13
	v_add_f32_e32 v9, v9, v13
	v_sub_f32_e32 v12, v18, v12
	v_add_f32_e32 v9, v12, v9
	v_add_f32_e32 v12, v16, v17
	v_add_f32_e32 v9, v19, v9
	v_sub_f32_e32 v13, v12, v16
	v_mul_f32_e32 v9, v14, v9
	v_sub_f32_e32 v13, v17, v13
	v_add_f32_e32 v9, v13, v9
	v_mul_f32_e32 v16, 0x3f317218, v8
	v_add_f32_e32 v13, v12, v9
	v_fma_f32 v17, v8, s6, -v16
	v_mul_f32_e32 v14, v13, v13
	v_fmac_f32_e32 v17, 0xb102e308, v8
	v_sub_f32_e32 v8, v13, v12
	v_fmamk_f32 v15, v14, 0x3e9b6dac, v1
	v_sub_f32_e32 v8, v9, v8
	v_add_f32_e32 v9, v16, v17
	v_fmaak_f32 v15, v14, v15, 0x3f2aaada
	v_sub_f32_e32 v12, v9, v16
	v_ldexp_f32 v16, v13, 1
	v_mul_f32_e32 v13, v13, v14
	v_mul_f32_e32 v13, v13, v15
	v_add_f32_e32 v14, v16, v13
	v_sub_f32_e32 v15, v14, v16
	v_ldexp_f32 v8, v8, 1
	v_sub_f32_e32 v13, v13, v15
	v_add_f32_e32 v8, v8, v13
	v_add_f32_e32 v13, v14, v8
	v_sub_f32_e32 v14, v13, v14
	v_sub_f32_e32 v8, v8, v14
	v_add_f32_e32 v14, v9, v13
	v_sub_f32_e32 v15, v14, v9
	v_sub_f32_e32 v16, v14, v15
	v_sub_f32_e32 v12, v17, v12
	v_sub_f32_e32 v9, v9, v16
	v_sub_f32_e32 v13, v13, v15
	v_add_f32_e32 v9, v13, v9
	v_add_f32_e32 v13, v12, v8
	v_sub_f32_e32 v15, v13, v12
	v_sub_f32_e32 v16, v13, v15
	v_sub_f32_e32 v12, v12, v16
	v_sub_f32_e32 v8, v8, v15
	v_add_f32_e32 v9, v13, v9
	v_add_f32_e32 v8, v8, v12
	v_add_f32_e32 v12, v14, v9
	v_sub_f32_e32 v13, v12, v14
	v_sub_f32_e32 v9, v9, v13
	v_add_f32_e32 v8, v8, v9
	s_mov_b32 s6, 0x7f800000
	v_add_f32_e32 v8, v12, v8
	v_cmp_neq_f32_e32 vcc, s6, v11
	s_mov_b32 s6, 0x33800000
	s_nop 0
	v_cndmask_b32_e32 v8, v210, v8, vcc
	v_cmp_ngt_f32_e32 vcc, -1.0, v11
	s_nop 1
	v_cndmask_b32_e32 v8, v211, v8, vcc
	v_cmp_neq_f32_e32 vcc, -1.0, v11
	s_nop 1
	v_cndmask_b32_e32 v8, v212, v8, vcc
	v_cmp_lt_f32_e64 vcc, |v11|, s6
	s_nop 1
	v_cndmask_b32_e32 v8, v8, v11, vcc
	v_cmp_lt_i32_e32 vcc, v215, v214
	v_add_f32_e32 v8, v10, v8
	v_mul_f32_e64 v9, v8, -v7
	v_cndmask_b32_e32 v10, v215, v213, vcc
	v_lshlrev_b32_e32 v10, 2, v10
	ds_bpermute_b32 v10, v10, v9
	v_cmp_gt_i32_e32 vcc, 4, v222
	s_waitcnt lgkmcnt(0)
	v_fma_f32 v7, v8, -v7, v10
	v_cndmask_b32_e32 v7, v7, v9, vcc
	v_cmp_lt_i32_e32 vcc, v216, v214
	s_nop 1
	v_cndmask_b32_e32 v9, v216, v213, vcc
	v_lshlrev_b32_e32 v9, 2, v9
	ds_bpermute_b32 v9, v9, v7
	v_cmp_gt_i32_e32 vcc, 8, v222
	s_waitcnt lgkmcnt(0)
	v_add_f32_e32 v9, v7, v9
	v_cndmask_b32_e32 v7, v9, v7, vcc
	v_cmp_lt_i32_e32 vcc, v217, v214
	s_nop 1
	v_cndmask_b32_e32 v9, v217, v213, vcc
	v_lshlrev_b32_e32 v9, 2, v9
	ds_bpermute_b32 v9, v9, v7
	v_cmp_gt_i32_e32 vcc, 16, v222
	s_waitcnt lgkmcnt(0)
	v_add_f32_e32 v9, v7, v9
	v_cndmask_b32_e32 v7, v9, v7, vcc
	v_cmp_lt_i32_e32 vcc, v218, v214
	s_nop 1
	v_cndmask_b32_e32 v9, v218, v213, vcc
	v_lshlrev_b32_e32 v9, 2, v9
	ds_bpermute_b32 v9, v9, v7
	v_cmp_lt_i32_e32 vcc, 59, v222
	s_waitcnt lgkmcnt(0)
	v_add_f32_e32 v9, v7, v9
	s_and_saveexec_b64 s[6:7], vcc
	v_lshl_add_u32 v10, v6, 2, s61
	ds_write_b32 v10, v9
	s_or_b64 exec, exec, s[6:7]
	v_cmp_gt_i32_e32 vcc, 32, v222
	s_waitcnt lgkmcnt(0)
	s_barrier
; __device__ __forceinline__ void ssd_chunk_unit(LAS unsigned char* ldsb, int unit, const bf16* PROJ, bf16* XACT, const float* DTRAW, const float* conv_w, const float* conv_b, const float* dt_bias, const float* a_log, ...
;     ...
;         float off = 0.f, tot = 0.f;
;         for (int w2 = 0; w2 < 8; ++w2) { const float wv = WT[w2 * 4 + hh]; tot += wv; if (w2 < wave) off += wv; }
;         v += off;
;         DTT[tid] = dtv; ACST[tid] = v; WTAB[hh * 128 + s] = __expf(tot - v); __hip_atomic_store(&ACS[(size_t)(tok0 + s) * 8 + H], v, __ATOMIC_RELAXED, __HIP_MEMORY_SCOPE_AGENT);
;         if (s == 127) __hip_atomic_store(&CDEC[bc * 8 + H], __expf(v), __ATOMIC_RELAXED, __HIP_MEMORY_SCOPE_AGENT);
	v_cndmask_b32_e32 v7, v9, v7, vcc
	v_lshl_add_u32 v9, v6, 2, 0
	v_add_u32_e32 v9, 0x1b000, v9
	ds_read2_b32 v[10:11], v9 offset1:4
	ds_read2_b32 v[12:13], v9 offset0:8 offset1:12
	v_readlane_b32 s6, v235, 60
	v_readlane_b32 s7, v235, 61
	v_lshlrev_b32_e32 v6, 9, v6
	s_waitcnt lgkmcnt(1)
	v_add_f32_e32 v10, 0, v10
	v_cndmask_b32_e64 v14, v10, 0, s[6:7]
	v_readlane_b32 s6, v235, 62
	v_add_f32_e32 v10, v10, v11
	v_add_f32_e32 v11, v11, v14
	v_readlane_b32 s7, v235, 63
	s_waitcnt lgkmcnt(0)
	v_add_f32_e32 v10, v10, v12
	v_lshl_add_u64 v[2:3], v[2:3], 2, s[52:53]
	v_cndmask_b32_e64 v11, v14, v11, s[6:7]
	v_readlane_b32 s6, v234, 0
	v_add_f32_e32 v12, v12, v11
	v_readlane_b32 s7, v234, 1
	s_nop 1
	v_cndmask_b32_e64 v11, v11, v12, s[6:7]
	v_readlane_b32 s6, v234, 2
	v_add_f32_e32 v12, v10, v13
	v_add_f32_e32 v10, v13, v11
	v_readlane_b32 s7, v234, 3
	s_nop 1
	v_cndmask_b32_e64 v13, v11, v10, s[6:7]
	ds_read2_b32 v[10:11], v9 offset0:16 offset1:20
	v_readlane_b32 s6, v234, 4
	v_readlane_b32 s7, v234, 5
	s_waitcnt lgkmcnt(0)
	v_add_f32_e32 v12, v12, v10
	v_add_f32_e32 v10, v10, v13
	v_cndmask_b32_e64 v10, v13, v10, s[6:7]
	v_readlane_b32 s6, v234, 6
	v_add_f32_e32 v12, v12, v11
	v_add_f32_e32 v11, v11, v10
	v_readlane_b32 s7, v234, 7
	s_nop 1
	v_cndmask_b32_e64 v13, v10, v11, s[6:7]
	ds_read2_b32 v[10:11], v9 offset0:24 offset1:28
	v_readlane_b32 s6, v234, 8
	v_readlane_b32 s7, v234, 9
	s_waitcnt lgkmcnt(0)
	v_add_f32_e32 v9, v12, v10
	v_add_f32_e32 v10, v10, v13
	v_cndmask_b32_e64 v10, v13, v10, s[6:7]
	v_readlane_b32 s6, v234, 10
	v_add_f32_e32 v9, v9, v11
	v_add_f32_e32 v11, v11, v10
	v_readlane_b32 s7, v234, 11
	s_nop 1
	v_cndmask_b32_e64 v10, v10, v11, s[6:7]
	v_add_f32_e32 v7, v7, v10
	v_lshl_add_u32 v10, v118, 2, 0
	v_add_u32_e32 v11, 0x1a000, v10
	ds_write_b32 v11, v8
	v_add_u32_e32 v8, 0x19800, v10
	ds_write_b32 v8, v7
	v_sub_f32_e32 v8, v9, v7
	v_mul_f32_e32 v8, 0x3fb8aa3b, v8
	v_exp_f32_e32 v8, v8
	v_lshlrev_b32_e32 v9, 2, v5
	s_movk_i32 s6, 0x7f
	v_add3_u32 v6, s14, v6, v9
	v_cmp_eq_u32_e32 vcc, s6, v5
	ds_write_b32 v6, v8
	global_store_dword v[2:3], v7, off
	s_and_saveexec_b64 s[6:7], vcc
	s_cbranch_execz .LBB0_173
	v_mul_f32_e32 v2, 0x3fb8aa3b, v7
	v_exp_f32_e32 v5, v2
	v_lshl_or_b32 v2, s60, 3, v4
	v_ashrrev_i32_e32 v3, 31, v2
	v_lshl_add_u64 v[2:3], v[2:3], 2, s[82:83]
	global_store_dword v[2:3], v5, off
